# v26 + component-boundary prefetch extended to sample units (K0/K1/Q/K2 prefetched, V0 stays in component 2's prologue)
# baseline (speedup 1.0000x reference)
;   #define DMA_K(t,slot) glds16s(Kb+(long)(t)*KVBLK*kp,ksrc,(unsigned)__builtin_amdgcn_readfirstlane(kdst+(slot)))
;   #define DMA_V(t,slot) do{ glds16s(Vb+(long)(t)*KVBLK*vp,vsrc,(unsigned)__builtin_amdgcn_readfirstlane(vdst+(slot))); \
;       if(VH==2) glds16s(Vb+(long)(t)*KVBLK*vp+64,vsrc,(unsigned)__builtin_amdgcn_readfirstlane(vdst+(slot)+8192)); }while(0)
; template<int VH,bool HAS_BIAS,int MODE> __device__ __forceinline__ void attn_unit2(const bf16*Qb,int qp,const bf16*__restrict__ Kb,int kp,const bf16*__restrict__ Vb,int vp,bf16*Ob,int op,int q0,int NT,const float*relb,char*shm,float lam,const float*subg,float gmul){
;     ...
;   DMA_K(0,0);DMA_V(0,0);DMA_K(1,KSL);
;   bf16x8 qr[4];
;   #pragma unroll
;   for(int d0=0;d0<4;++d0)qr[d0]=*reinterpret_cast<const bf16x8*>(&Qw[(long)r32*qp+d0*16+hi*8]);
;   DMA_K(2,2*KSL);
; __global__ void __launch_bounds__(NWAVES * 64, 2) mega_fwd(Args args) {
;     ...
;                 attn_body::attn_unit2<2, true, 1>((const attn_body::bf16*)(Qb + tok0 * 1024 + (2 * h) * 64), 1024, (const attn_body::bf16*)(Kb + tok0 * 1024 + (2 * h) * 64), 1024,
;                     (const attn_body::bf16*)(Vb + tok0 * 1024 + h * 128), 1024, (attn_body::bf16*)(Ob + tok0 * 1024 + h * 128), 1024, qb * 256, NT, ap->in[10] + h, (char*)lds + RING_OFF, lam, ap->in[23], 1.0f - LAMBDA_INIT1);
;                 attn_body::attn_unit2<2, true, 2>((const attn_body::bf16*)(Qb + tok0 * 1024 + (2 * h + 1) * 64), 1024, (const attn_body::bf16*)(Kb + tok0 * 1024 + (2 * h + 1) * 64), 1024,
;                     (const attn_body::bf16*)(Vb + tok0 * 1024 + h * 128), 1024, (attn_body::bf16*)(Ob + tok0 * 1024 + h * 128), 1024, qb * 256, NT, ap->in[10] + h, (char*)lds + RING_OFF, lam, ap->in[23], 1.0f - LAMBDA_INIT1); }
.LBB0_1139:
	s_cmp_lg_u32 s69, 32
	s_cbranch_scc1 .Lnbp_sample
	s_waitcnt lgkmcnt(0)
	s_barrier
	s_add_u32 s98, s44, 0x80
	s_addc_u32 s99, s45, 0
	s_mov_b32 m0, s33
	s_nop 0
	global_load_lds_dwordx4 v202, s[98:99]
	s_add_i32 m0, s33, 0x8000
	s_nop 0
	global_load_lds_dwordx4 v203, s[46:47]
	s_add_i32 m0, s33, 0xa000
	s_nop 0
	global_load_lds_dwordx4 v203, s[48:49]
	s_add_u32 s98, s44, 0x20080
	s_addc_u32 s99, s45, 0
	s_add_i32 m0, s33, 0x2000
	s_nop 0
	global_load_lds_dwordx4 v202, s[98:99]
	v_readfirstlane_b32 s98, v184
	s_nop 3
	s_ashr_i32 s98, s98, 6
	s_lshl_b32 s98, s98, 5
	s_add_i32 s98, s98, s77
	s_ashr_i32 s99, s98, 31
	s_lshl_b64 s[98:99], s[98:99], 11
	s_add_u32 s100, s75, s98
	s_addc_u32 s101, s76, s99
	v_and_b32_e32 v253, 31, v184
	v_bfe_u32 v254, v184, 5, 1
	v_lshlrev_b32_e32 v253, 11, v253
	v_lshl_or_b32 v253, v254, 4, v253
	global_load_dwordx4 v[158:161], v253, s[100:101] offset:128
	global_load_dwordx4 v[154:157], v253, s[100:101] offset:160
	global_load_dwordx4 v[150:153], v253, s[100:101] offset:192
	global_load_dwordx4 v[146:149], v253, s[100:101] offset:224
	s_add_u32 s98, s44, 0x40080
	s_addc_u32 s99, s45, 0
	s_add_i32 m0, s33, 0x4000
	s_nop 0
	global_load_lds_dwordx4 v202, s[98:99]
	s_branch .Lnbp_none
.Lnbp_sample:
	s_add_u32 s98, s44, 0x80
	s_addc_u32 s99, s45, 0
	s_mov_b32 m0, s33
	s_nop 0
	global_load_lds_dwordx4 v202, s[98:99]
	s_add_u32 s98, s44, 0x20080
	s_addc_u32 s99, s45, 0
	s_add_i32 m0, s33, 0x2000
	s_nop 0
	global_load_lds_dwordx4 v202, s[98:99]
	v_readfirstlane_b32 s98, v184
	s_nop 3
	s_ashr_i32 s98, s98, 6
	s_lshl_b32 s98, s98, 5
	s_add_i32 s98, s98, s77
	s_ashr_i32 s99, s98, 31
	s_lshl_b64 s[98:99], s[98:99], 11
	s_add_u32 s100, s75, s98
	s_addc_u32 s101, s76, s99
	v_and_b32_e32 v253, 31, v184
	v_bfe_u32 v254, v184, 5, 1
	v_lshlrev_b32_e32 v253, 11, v253
	v_lshl_or_b32 v253, v254, 4, v253
	global_load_dwordx4 v[158:161], v253, s[100:101] offset:128
	global_load_dwordx4 v[154:157], v253, s[100:101] offset:160
	global_load_dwordx4 v[150:153], v253, s[100:101] offset:192
	global_load_dwordx4 v[146:149], v253, s[100:101] offset:224
	s_add_u32 s98, s44, 0x40080
	s_addc_u32 s99, s45, 0
	s_add_i32 m0, s33, 0x4000
	s_nop 0
	global_load_lds_dwordx4 v202, s[98:99]

;   #define DMA_K(t,slot) glds16s(Kb+(long)(t)*KVBLK*kp,ksrc,(unsigned)__builtin_amdgcn_readfirstlane(kdst+(slot)))
;   #define DMA_V(t,slot) do{ glds16s(Vb+(long)(t)*KVBLK*vp,vsrc,(unsigned)__builtin_amdgcn_readfirstlane(vdst+(slot))); \
;       if(VH==2) glds16s(Vb+(long)(t)*KVBLK*vp+64,vsrc,(unsigned)__builtin_amdgcn_readfirstlane(vdst+(slot)+8192)); }while(0)
; template<int VH,bool HAS_BIAS,int MODE> __device__ __forceinline__ void attn_unit2(const bf16*Qb,int qp,const bf16*__restrict__ Kb,int kp,const bf16*__restrict__ Vb,int vp,bf16*Ob,int op,int q0,int NT,const float*relb,char*shm,float lam,const float*subg,float gmul){
;     ...
;   DMA_K(0,0);DMA_V(0,0);DMA_K(1,KSL);
;   bf16x8 qr[4];
;   #pragma unroll
;   for(int d0=0;d0<4;++d0)qr[d0]=*reinterpret_cast<const bf16x8*>(&Qw[(long)r32*qp+d0*16+hi*8]);
;   DMA_K(2,2*KSL);
.LBB0_1153:
	s_or_b64 exec, exec, s[54:55]
	s_add_u32 s8, s44, 0x80
	s_addc_u32 s9, s45, 0
	s_ashr_i32 s54, s81, 6
	s_lshl_b32 s6, s54, 5
	s_add_i32 s6, s6, s77
	s_ashr_i32 s7, s6, 31
	s_lshl_b64 s[10:11], s[6:7], 11
	s_add_u32 s12, s75, s10
	v_and_b32_e32 v197, 63, v184
	s_addc_u32 s13, s76, s11
	s_lshl_b32 s7, s54, 4
	v_bfe_u32 v2, v184, 2, 4
	v_lshl_add_u32 v206, v197, 11, s7
	v_and_or_b32 v2, s7, 48, v2
	s_ashr_i32 s7, s81, 3
	s_and_b32 s7, s7, 0x7fffffe0
	v_lshl_add_u32 v2, v2, 10, s7
	s_lshl_b32 s7, s54, 10
	s_cmp_lg_u32 0, -1
	s_cselect_b32 s14, 0, 0
	s_add_i32 s33, s7, s14
	s_add_i32 s14, s6, 0xffffffa6
	s_add_i32 s57, s33, 0x8000
	s_ashr_i32 s14, s14, 6
	v_lshlrev_b32_e32 v3, 3, v184
	s_cmpk_gt_i32 s6, 0x59
	v_and_b32_e32 v199, 24, v3
	s_cselect_b32 s55, s14, 0
	s_add_i32 s14, s6, 0xb9
	v_or_b32_e32 v2, v2, v199
	s_ashr_i32 s56, s14, 6
	v_lshlrev_b32_e32 v207, 1, v2
	v_and_b32_e32 v185, 31, v184
	s_add_i32 s14, s33, 0xa000
	v_bfe_u32 v35, v184, 5, 1
	s_add_u32 s40, s44, 0x20080
	v_lshlrev_b32_e32 v2, 11, v185
	s_addc_u32 s41, s45, 0
	s_add_i32 s14, s33, 0x2000
	v_lshl_or_b32 v2, v35, 4, v2
	s_add_u32 s12, s44, 0x40080
	v_lshlrev_b32_e32 v194, 10, v35
	v_lshlrev_b32_e32 v2, 4, v185
	s_addc_u32 s13, s45, 0
	s_add_i32 s14, s33, 0x4000
	v_add3_u32 v205, 0, v194, v2
	s_cmp_eq_u32 s69, 32
	s_cbranch_scc1 .Lnbp_have
	s_add_i32 m0, s33, 0x8000
	s_nop 0
	global_load_lds_dwordx4 v207, s[46:47]
	s_add_i32 m0, s33, 0xa000
	s_nop 0
	global_load_lds_dwordx4 v207, s[48:49]
